# GLA pass3 value-tile transpose only: DPP lane-pair packing to 32-bit LDS writes
# baseline (speedup 1.0000x reference)
.LBB0_734:
	s_abs_i32 s1, s74
	v_readlane_b32 s2, v255, 40
	s_mul_hi_u32 s2, s1, s2
	s_mul_i32 s3, s2, s41
	s_sub_i32 s1, s1, s3
	s_ashr_i32 s0, s74, 31
	s_add_i32 s3, s2, 1
	s_sub_i32 s8, s1, s41
	s_cmp_ge_u32 s1, s41
	s_cselect_b32 s2, s3, s2
	s_cselect_b32 s1, s8, s1
	s_add_i32 s3, s2, 1
	s_cmp_ge_u32 s1, s41
	s_cselect_b32 s1, s3, s2
	s_xor_b32 s1, s1, s0
	s_sub_i32 s1, s1, s0
	s_and_b32 s0, s1, 3
	s_ashr_i32 s1, s1, 2
	s_sub_i32 s75, 1, s1
	s_lshl_b32 s2, s21, 6
	v_mov_b32_e32 v10, v207
	s_cmp_lt_i32 s21, 4
	s_cselect_b32 s22, s7, s6
	v_lshlrev_b32_e32 v0, 4, v10
	v_and_b32_e32 v66, 0x70, v0
	s_add_i32 s22, s22, s2
	v_mov_b32_e32 v0, v207
	s_barrier
	s_cmp_lg_u32 s1, 1
	v_and_b32_e32 v6, 63, v0
	v_or_b32_e32 v1, s22, v6
	s_movk_i32 s2, 0x1200
	s_cselect_b64 s[96:97], -1, 0
	s_lshl_b32 s20, s0, 7
	s_lshl_b32 s26, s0, 8
	v_mul_lo_u32 v128, v1, s2
	s_cmp_eq_u32 s1, 1
	s_movk_i32 s1, 0x800
	v_ashrrev_i32_e32 v0, 2, v0
	v_lshl_add_u64 v[2:3], v[128:129], 1, s[36:37]
	s_cselect_b32 s94, s1, 0x1c00
	s_mov_b32 s95, 0
	v_and_b32_e32 v0, -16, v0
	v_lshl_add_u64 v[2:3], v[2:3], 0, s[94:95]
	v_lshl_add_u64 v[2:3], v[2:3], 0, s[26:27]
	v_ashrrev_i32_e32 v1, 31, v0
	v_lshl_add_u64 v[4:5], v[0:1], 1, v[2:3]
	s_movk_i32 s8, 0x90
	v_lshlrev_b32_e32 v12, 1, v6
	v_mul_lo_u32 v13, v0, s8
	global_load_dwordx4 v[0:3], v[4:5], off
	s_nop 0
	global_load_dwordx4 v[4:7], v[4:5], off offset:16
	v_ashrrev_i32_e32 v67, 3, v10
	v_mov_b64_e32 v[8:9], s[36:37]
	v_readlane_b32 s4, v252, 12
	v_add_u32_e32 v64, s22, v67
	v_mad_i64_i32 v[68:69], s[2:3], v64, s14, v[8:9]
	v_add3_u32 v14, s4, v12, v13
	v_add3_u32 v12, s4, v13, v12
	s_cselect_b32 s94, 0, 0x1000
	v_lshlrev_b32_e32 v128, 1, v66
	v_ashrrev_i32_e32 v11, 6, v10
	v_and_b32_e32 v92, 31, v10
	v_and_b32_e32 v94, 3, v11
	s_lshl_b32 s1, s75, 3
	s_lshl_b32 s2, s0, 1
	s_or_b32 s23, s1, s2
	v_bfe_u32 v93, v10, 5, 1
	s_cmp_gt_i32 s21, 3
	s_cselect_b32 s1, 0x87, 3
	v_lshl_add_u32 v95, v66, 2, 0
	v_readlane_b32 s5, v255, 1
	v_bfi_b32 v8, -16, v67, v10
	v_cvt_f32_ubyte0_e32 v96, s0
	v_ashrrev_i32_e32 v65, 31, v64
	s_mov_b64 s[92:93], -1
	s_waitcnt vmcnt(0) lgkmcnt(0)
	v_and_b32_e32 v164, 1, v207
	v_sub_u32_e32 v164, 0, v164
	v_and_b32_e32 v165, 0x6060606, v164
	v_xor_b32_e32 v165, 0x5040100, v165
	v_and_b32_e32 v166, 0x8e, v164
	v_add_u32_e32 v166, v166, v14
	v_mov_b32_dpp v167, v0 quad_perm:[1,0,3,2] row_mask:0xf bank_mask:0xf
	v_perm_b32 v167, v167, v0, v165
	ds_write_b32 v166, v167
	v_mov_b32_dpp v168, v1 quad_perm:[1,0,3,2] row_mask:0xf bank_mask:0xf
	v_perm_b32 v168, v168, v1, v165
	ds_write_b32 v166, v168 offset:288
	v_mov_b32_dpp v167, v2 quad_perm:[1,0,3,2] row_mask:0xf bank_mask:0xf
	v_perm_b32 v167, v167, v2, v165
	ds_write_b32 v166, v167 offset:576
	v_mov_b32_dpp v168, v3 quad_perm:[1,0,3,2] row_mask:0xf bank_mask:0xf
	v_perm_b32 v168, v168, v3, v165
	ds_write_b32 v166, v168 offset:864
	v_mov_b32_dpp v167, v4 quad_perm:[1,0,3,2] row_mask:0xf bank_mask:0xf
	v_perm_b32 v167, v167, v4, v165
	ds_write_b32 v166, v167 offset:1152
	v_mov_b32_dpp v168, v5 quad_perm:[1,0,3,2] row_mask:0xf bank_mask:0xf
	v_perm_b32 v168, v168, v5, v165
	ds_write_b32 v166, v168 offset:1440
	v_mov_b32_dpp v167, v6 quad_perm:[1,0,3,2] row_mask:0xf bank_mask:0xf
	v_perm_b32 v167, v167, v6, v165
	ds_write_b32 v166, v167 offset:1728
	v_mov_b32_dpp v168, v7 quad_perm:[1,0,3,2] row_mask:0xf bank_mask:0xf
	v_perm_b32 v168, v168, v7, v165
	ds_write_b32 v166, v168 offset:2016
	v_lshl_add_u64 v[0:1], v[68:69], 0, s[94:95]
	v_lshl_add_u64 v[0:1], v[0:1], 0, s[26:27]
	v_lshl_add_u64 v[4:5], v[0:1], 0, v[128:129]
	global_load_dwordx4 v[0:3], v[4:5], off
	s_nop 0
	global_load_dwordx4 v[4:7], v[4:5], off offset:16
	s_sub_i32 s94, s1, s21
	v_readlane_b32 s1, v255, 0
	s_add_u32 s2, s36, s26
	s_addc_u32 s3, s37, 0
	s_waitcnt vmcnt(0) lgkmcnt(0)
	v_lshlrev_b32_e32 v70, 16, v0
	v_lshlrev_b32_e32 v78, 16, v4
	v_and_b32_e32 v79, 0xffff0000, v4
	v_lshl_or_b32 v4, v94, 5, v92
	v_and_b32_e32 v71, 0xffff0000, v0
	v_lshlrev_b32_e32 v72, 16, v1
	v_and_b32_e32 v73, 0xffff0000, v1
	v_lshlrev_b32_e32 v0, 8, v4
	v_mov_b32_e32 v1, v129
	v_lshlrev_b32_e32 v74, 16, v2
	v_and_b32_e32 v75, 0xffff0000, v2
	v_lshlrev_b32_e32 v76, 16, v3
	v_and_b32_e32 v77, 0xffff0000, v3
	v_lshl_add_u64 v[0:1], s[84:85], 0, v[0:1]
	v_lshlrev_b32_e32 v2, 4, v93
	v_mov_b32_e32 v3, v129
	v_lshl_add_u64 v[86:87], v[0:1], 0, v[2:3]
	v_add_u32_e32 v3, s4, v2
	s_movk_i32 s4, 0x110
	v_lshlrev_b32_e32 v80, 16, v5
	v_and_b32_e32 v81, 0xffff0000, v5
	v_sub_u32_e32 v0, v95, v128
	v_add_u32_e32 v1, s5, v2
	v_add_u32_e32 v5, s1, v2
	v_mul_lo_u32 v2, v67, s4
	v_add_u32_e32 v97, v0, v2
	v_add3_u32 v98, s1, v128, v2
	v_and_b32_e32 v2, 48, v10
	v_add_u32_e32 v2, 0, v2
	v_mad_u64_u32 v[88:89], s[0:1], v8, s4, v[2:3]
	v_lshrrev_b32_e32 v8, 2, v10
	v_and_b32_e32 v8, 12, v8
	v_lshlrev_b32_e32 v84, 16, v7
	v_and_b32_e32 v85, 0xffff0000, v7
	v_lshlrev_b32_e32 v0, 5, v11
	v_and_b32_e32 v7, 15, v10
	v_and_or_b32 v8, v67, -16, v8
	v_and_or_b32 v0, v0, 32, v7
	v_or_b32_e32 v13, 1, v8
	v_or_b32_e32 v14, 2, v8
	v_or_b32_e32 v15, 3, v8
	s_movk_i32 s0, 0xffe0
	v_mul_u32_u24_e32 v7, 0x110, v0
	v_lshl_add_u32 v11, v0, 1, s5
	v_cmp_ge_i32_e64 s[42:43], v0, v8
	v_cmp_le_i32_e64 s[44:45], v0, v8
	v_cmp_gt_i32_e64 s[46:47], v0, v8
	v_cmp_le_i32_e64 s[48:49], v0, v13
	v_cmp_ge_i32_e64 s[50:51], v0, v14
	v_cmp_le_i32_e64 s[52:53], v0, v14
	v_cmp_ge_i32_e64 s[54:55], v0, v15
	v_cmp_le_i32_e64 s[56:57], v0, v15
	v_or_b32_e32 v0, 16, v0
	v_bfi_b32 v9, s0, v67, v10
	v_mul_lo_u32 v12, v8, s8
	v_lshlrev_b32_e32 v16, 1, v0
	v_lshlrev_b32_e32 v82, 16, v6
	v_and_b32_e32 v83, 0xffff0000, v6
	v_lshlrev_b32_e32 v6, 9, v67
	v_mul_lo_u32 v10, v9, s8
	v_mul_u32_u24_e32 v4, 0x90, v4
	v_mul_lo_u32 v9, v9, s4
	v_cmp_ge_i32_e64 s[58:59], v0, v8
	v_cmp_le_i32_e64 s[60:61], v0, v8
	v_add3_u32 v99, s5, v12, v16
	v_cmp_gt_i32_e64 s[62:63], v0, v8
	v_cmp_le_i32_e64 s[64:65], v0, v13
	v_cmp_ge_i32_e64 s[66:67], v0, v14
	v_cmp_le_i32_e64 s[68:69], v0, v14
	v_cmp_ge_i32_e64 s[70:71], v0, v15
	v_cmp_le_i32_e64 s[72:73], v0, v15
	v_mov_b32_e32 v0, 0
	v_and_b32_e32 v89, 0xffffffe0, v67
	v_add_u32_e32 v100, 0x90, v99
	v_add_u32_e32 v101, 0x120, v99
	v_add_u32_e32 v102, 0x1b0, v99
	v_add_u32_e32 v103, v95, v6
	v_add_u32_e32 v104, v2, v7
	v_add_u32_e32 v105, v11, v12
	v_add_u32_e32 v106, v1, v10
	v_add_u32_e32 v107, v3, v4
	v_add_u32_e32 v108, v5, v9
	v_mov_b32_e32 v1, v0
	v_mov_b32_e32 v2, v0
	v_mov_b32_e32 v3, v0
	v_mov_b32_e32 v4, v0
	v_mov_b32_e32 v5, v0
	v_mov_b32_e32 v6, v0
	v_mov_b32_e32 v7, v0
	v_mov_b32_e32 v8, v0
	v_mov_b32_e32 v9, v0
	v_mov_b32_e32 v10, v0
	v_mov_b32_e32 v11, v0
	v_mov_b32_e32 v12, v0
	v_mov_b32_e32 v13, v0
	v_mov_b32_e32 v14, v0
	v_mov_b32_e32 v15, v0
	s_branch .LBB0_736
